# fused-LN panel counter wait polls back to back; timeout clock read every 32nd poll only
# baseline (speedup 1.0000x reference)
;     __device__ __forceinline__ void fused(f32x4 (&acc)[2][2][4][2], const GUnit& u, int wr, int wc, int fr, int fq, LAS unsigned char* lds, int wid, int lane) const {
;     ...
;         if (wid == 0) {
;             bool dead = false; const unsigned long long t0 = __builtin_amdgcn_s_memrealtime();
;             for (;;) {
;                 if ((unsigned)__builtin_amdgcn_readfirstlane(__hip_atomic_load(cnt + 64 * u.pm, __ATOMIC_RELAXED, __HIP_MEMORY_SCOPE_AGENT)) >= 32u) break;
;                 if (__builtin_amdgcn_s_memrealtime() - t0 > 2000000ull) {
.LBB0_454:
	s_or_b64 exec, exec, s[2:3]
	v_readlane_b32 s2, v251, 16
	v_readlane_b32 s3, v251, 17
	s_andn2_b64 vcc, exec, s[2:3]
	s_cbranch_vccnz .LBB0_468
	s_mov_b32 s99, 0
	s_memrealtime s[2:3]
	s_lshl_b32 s8, s37, 6
	s_ashr_i32 s9, s8, 31
	s_lshl_b64 s[8:9], s[8:9], 2
	s_add_u32 s8, s10, s8
	s_addc_u32 s9, s11, s9
	s_branch .LBB0_458

;     __device__ __forceinline__ void fused(f32x4 (&acc)[2][2][4][2], const GUnit& u, int wr, int wc, int fr, int fq, LAS unsigned char* lds, int wid, int lane) const {
;     ...
;             for (;;) {
;                 if ((unsigned)__builtin_amdgcn_readfirstlane(__hip_atomic_load(cnt + 64 * u.pm, __ATOMIC_RELAXED, __HIP_MEMORY_SCOPE_AGENT)) >= 32u) break;
;                 if (__builtin_amdgcn_s_memrealtime() - t0 > 2000000ull) {
;                     if (lane == 0) { unsigned expect = 0u; __hip_atomic_compare_exchange_strong(tmo + 1, &expect, 0x700u | (unsigned)(u.pm & 0xff), __ATOMIC_RELAXED, __ATOMIC_RELAXED, __HIP_MEMORY_SCOPE_AGENT);
;                                      __hip_atomic_store(tmo, 1u, __ATOMIC_RELAXED, __HIP_MEMORY_SCOPE_AGENT); }
;                     dead = true; break; }
;                 __builtin_amdgcn_s_sleep(2);
;             }
.LBB0_458:
	global_load_dword v32, v33, s[8:9] sc1
	s_mov_b64 s[10:11], -1
	s_waitcnt vmcnt(0)
	v_readfirstlane_b32 s12, v32
	s_cmp_gt_u32 s12, 31
	s_mov_b64 s[12:13], -1
	s_cbranch_scc1 .LBB0_457
	s_add_i32 s99, s99, 1
	s_and_b32 s12, s99, 31
	s_cmp_eq_u32 s12, 0
	s_mov_b64 s[12:13], -1
	s_cbranch_scc1 .Lln_poll_clock
	s_sleep 1
	s_branch .LBB0_458
.Lln_poll_clock:
	s_memrealtime s[10:11]
	s_waitcnt lgkmcnt(0)
	s_sub_u32 s10, s10, s2
	s_subb_u32 s11, s11, s3
	v_cmp_lt_u64_e32 vcc, s[10:11], v[230:231]
	s_cbranch_vccz .LBB0_456
	s_mov_b64 s[12:13], 0
	s_sleep 2
	s_branch .LBB0_456
